# barrier before the next layer's weight conversion also split-phase: only items that overwrite the MLP weights wait for the global generation
# speedup vs baseline: 1.0280x; 1.0028x over previous
; #define LAS __attribute__((address_space(3)))
; __global__ void __launch_bounds__(512, 2) fwd_mega(Params p, int ph_lo, int ph_hi, int coop) {
;     ...
;   if (coop) {
;     if (threadIdx.x == 0) xb_words = make_uint4(0u, 0u, 0u, 0u);
;     __syncthreads();
;     xb = xcd_barrier_post((unsigned*)(p.ws + OFF_BAR), (volatile LAS unsigned*)&xb_words);
;   }
_Z8fwd_mega6Paramsiii:
	s_mov_b32 s100, 0
	s_load_dwordx8 s[88:95], s[0:1], 0xc0
	v_writelane_b32 v244, s2, 0
	s_waitcnt lgkmcnt(0)
	s_cmp_lg_u32 s94, 0
	s_cselect_b64 s[2:3], -1, 0
	v_writelane_b32 v244, s2, 1
	s_cmp_eq_u32 s94, 0
	s_nop 0
	v_writelane_b32 v244, s3, 2
	s_cbranch_scc1 .LBB0_7
	v_and_b32_e32 v1, 0x3ff, v0
	v_cmp_eq_u32_e32 vcc, 0, v1
	s_and_saveexec_b64 s[2:3], vcc
	v_mov_b32_e32 v2, 0
	v_mov_b32_e32 v3, v2
	v_mov_b32_e32 v4, v2
	v_mov_b32_e32 v5, v2
	ds_write_b128 v2, v[2:5] offset:3072
	s_or_b64 exec, exec, s[2:3]
	s_add_u32 s2, s90, 0xf588000
	s_addc_u32 s3, s91, 0
	v_writelane_b32 v244, s2, 51
	s_waitcnt lgkmcnt(0)
	s_barrier
	v_writelane_b32 v244, s3, 52
	s_getreg_b32 s2, hwreg(HW_REG_XCC_ID, 0, 4)
	s_and_b32 s8, s2, 15
	s_and_saveexec_b64 s[2:3], vcc
	s_cbranch_execz .LBB0_6
	s_mov_b64 s[4:5], exec
	v_mbcnt_lo_u32_b32 v1, s4, 0
	v_mbcnt_hi_u32_b32 v1, s5, v1
	v_cmp_eq_u32_e32 vcc, 0, v1
	s_and_b64 s[6:7], exec, vcc
	s_mov_b64 exec, s[6:7]
	s_cbranch_execz .LBB0_6
	s_bcnt1_i32_b64 s4, s[4:5]
	s_lshl_b32 s6, s8, 8
	v_mov_b32_e32 v2, s4
	v_readlane_b32 s4, v244, 51
	v_mov_b32_e32 v1, s6
	v_readlane_b32 s5, v244, 52
	s_nop 4
	global_atomic_add v1, v2, s[4:5] offset:1024
	v_readlane_b32 s6, v244, 0
	s_and_b32 s6, s6, 7
	s_lshl_b32 s6, s6, 2
	s_add_i32 s6, s6, 0x3600
	s_lshl_b32 s7, 1, s8
	v_mov_b32_e32 v3, s7
	v_mov_b32_e32 v4, s6
	global_atomic_or v4, v3, s[4:5]

; DEVI int get_tid() { int t = threadIdx.x & 255; asm volatile("" : "+v"(t)); return t; }
; DEVI int vblk() { return (int)blockIdx.x * 2 + vhalf(); }
; DEVI int vgrid() { return (int)gridDim.x * 2; }
; DEVI void rms_rows(const float* __restrict__ x, float* __restrict__ ssq, bfu* __restrict__ dst, int item) {
;   const int lane = get_tid() & 63, wid = get_tid() >> 6;
;   float4 v[4][4];
; #pragma unroll
;   for (int r = 0; r < 4; ++r) {
;     const float4* xr = (const float4*)(x + ((long)item * 16 + wid * 4 + r) * 1024);
; #pragma unroll
;     for (int i = 0; i < 4; ++i) v[r][i] = xr[lane + 64 * i];
;   }
; #pragma unroll
;   for (int r = 0; r < 4; ++r) {
;     long row = (long)item * 16 + wid * 4 + r;
;     float ss = 0.f;
; #pragma unroll
;     for (int i = 0; i < 4; ++i) ss += v[r][i].x * v[r][i].x + v[r][i].y * v[r][i].y + v[r][i].z * v[r][i].z + v[r][i].w * v[r][i].w;
;     ss = wave_sum(ss);
;     if (lane == 0) *(float4*)(ssq + row * 4) = make_float4(ss, 0.f, 0.f, 0.f);
; DEVI void phase1(const Params& p, int l, char* lds) {
;     ...
;   for (int item = vblk(); item < n_items; item += vgrid()) {
;     int i = item;
;     if (i < P1_CVT) {
.LBB0_782:
	s_cmp_eq_u32 s100, 0
	s_cbranch_scc1 .Lp1_released
	s_cmpk_lt_i32 s23, 0x900
	s_cbranch_scc1 .Lp1_released
	v_readlane_b32 vcc_lo, v242, 28
	v_readlane_b32 vcc_hi, v242, 29
.Lp1_poll:
	s_nop 4
	global_load_dword v124, v1, vcc sc1
	s_waitcnt vmcnt(0)
	v_readfirstlane_b32 s101, v124
	s_cmp_ge_u32 s101, s100
	s_cbranch_scc1 .Lp1_ok
	s_sleep 1
	s_branch .Lp1_poll
.Lp1_ok:
	s_mov_b32 s100, 0
.Lp1_released:
	s_cmpk_gt_i32 s23, 0x1183
	s_mov_b64 s[0:1], -1
	s_cbranch_scc0 .LBB0_803
	s_cmpk_gt_u32 s23, 0x1185
	s_cbranch_scc0 .LBB0_793
	v_mov_b32_e32 v0, v221
	s_lshl_b32 s0, s23, 4
	v_and_b32_e32 v78, 63, v0
	v_mov_b32_e32 v0, v221
	s_add_i32 s30, s0, 0xfffee7a0
	v_ashrrev_i32_e32 v0, 4, v0
	v_and_b32_e32 v2, -4, v0
	v_ashrrev_i32_e32 v3, 31, v2
	v_lshl_add_u64 v[72:73], v[2:3], 0, s[30:31]
	v_lshlrev_b64 v[2:3], 12, v[72:73]
	v_lshl_add_u64 v[2:3], s[4:5], 0, v[2:3]
	v_lshlrev_b32_e32 v0, 4, v78
	v_lshl_add_u64 v[2:3], v[2:3], 0, v[0:1]
	global_load_dwordx4 v[48:51], v[2:3], off nt
	global_load_dwordx4 v[40:43], v[2:3], off offset:1024 nt
	global_load_dwordx4 v[44:47], v[2:3], off offset:2048 nt
	global_load_dwordx4 v[36:39], v[2:3], off offset:3072 nt
	v_or_b32_e32 v74, 1, v72
	v_mov_b32_e32 v75, v73
	v_or_b32_e32 v70, 2, v72
	v_mov_b32_e32 v71, v73
	v_or_b32_e32 v68, 3, v72
	v_mov_b32_e32 v69, v73
	v_lshlrev_b64 v[2:3], 12, v[74:75]
	v_lshlrev_b64 v[4:5], 12, v[70:71]
	v_lshlrev_b64 v[6:7], 12, v[68:69]
	v_lshl_add_u64 v[2:3], s[4:5], 0, v[2:3]
	v_lshl_add_u64 v[4:5], s[4:5], 0, v[4:5]
	v_lshl_add_u64 v[6:7], s[4:5], 0, v[6:7]
	v_lshl_add_u64 v[2:3], v[2:3], 0, v[0:1]
	v_lshl_add_u64 v[4:5], v[4:5], 0, v[0:1]
	v_lshl_add_u64 v[6:7], v[6:7], 0, v[0:1]
	global_load_dwordx4 v[64:67], v[2:3], off nt
	global_load_dwordx4 v[60:63], v[2:3], off offset:1024 nt
	global_load_dwordx4 v[56:59], v[2:3], off offset:2048 nt
	global_load_dwordx4 v[52:55], v[2:3], off offset:3072 nt
	global_load_dwordx4 v[32:35], v[4:5], off nt
	global_load_dwordx4 v[28:31], v[4:5], off offset:1024 nt
	global_load_dwordx4 v[24:27], v[4:5], off offset:2048 nt
	global_load_dwordx4 v[20:23], v[4:5], off offset:3072 nt
	global_load_dwordx4 v[16:19], v[6:7], off nt
	global_load_dwordx4 v[12:15], v[6:7], off offset:1024 nt
	global_load_dwordx4 v[8:11], v[6:7], off offset:2048 nt
	s_nop 0
	global_load_dwordx4 v[4:7], v[6:7], off offset:3072 nt
	v_and_b32_e32 v0, 64, v225
	v_xor_b32_e32 v2, 32, v225
	v_add_u32_e32 v0, 64, v0
	v_cmp_lt_i32_e32 vcc, v2, v0
	s_waitcnt vmcnt(0)
	v_pk_mul_f32 v[76:77], v[50:51], v[50:51]
	v_cndmask_b32_e32 v2, v225, v2, vcc
	v_lshlrev_b32_e32 v79, 2, v2
	v_pk_mul_f32 v[2:3], v[48:49], v[48:49]
	v_pk_mul_f32 v[80:81], v[40:41], v[40:41]
	v_pk_mul_f32 v[82:83], v[42:43], v[42:43]
	v_pk_mul_f32 v[84:85], v[44:45], v[44:45]
	v_add_f32_e32 v80, v80, v81
	v_add_f32_e32 v2, v2, v3
	v_pk_mul_f32 v[86:87], v[46:47], v[46:47]
	v_pk_mul_f32 v[88:89], v[36:37], v[36:37]
	v_add_f32_e32 v3, v84, v85
	v_add_f32_e32 v80, v80, v82
	v_add_f32_e32 v2, v2, v76
	v_pk_mul_f32 v[90:91], v[38:39], v[38:39]
	v_add_f32_e32 v81, v88, v89
	v_add_f32_e32 v3, v3, v86
	v_add_f32_e32 v80, v80, v83
	v_add_f32_e32 v2, v2, v77
	v_add_f32_e32 v76, v81, v90
	v_add_f32_e32 v3, v3, v87
	v_add_f32_e32 v2, v2, v80
	v_add_f32_e32 v76, v76, v91
	v_add_f32_e32 v2, v2, v3
	v_add_f32_e32 v2, v2, v76
	ds_bpermute_b32 v3, v79, v2
	v_xor_b32_e32 v76, 16, v225
	v_cmp_lt_i32_e32 vcc, v76, v0
	s_waitcnt lgkmcnt(0)
	v_add_f32_e32 v2, v2, v3
	v_cndmask_b32_e32 v76, v225, v76, vcc
	v_lshlrev_b32_e32 v80, 2, v76
	ds_bpermute_b32 v3, v80, v2
	v_xor_b32_e32 v76, 8, v225
	v_cmp_lt_i32_e32 vcc, v76, v0
	s_waitcnt lgkmcnt(0)
	v_add_f32_e32 v2, v2, v3
	v_cndmask_b32_e32 v76, v225, v76, vcc
	v_lshlrev_b32_e32 v81, 2, v76
	ds_bpermute_b32 v3, v81, v2
	v_xor_b32_e32 v76, 4, v225
	v_cmp_lt_i32_e32 vcc, v76, v0
	s_waitcnt lgkmcnt(0)
	v_add_f32_e32 v2, v2, v3
	v_cndmask_b32_e32 v76, v225, v76, vcc
	v_lshlrev_b32_e32 v82, 2, v76
	ds_bpermute_b32 v3, v82, v2
	v_xor_b32_e32 v76, 2, v225
	v_cmp_lt_i32_e32 vcc, v76, v0
	s_waitcnt lgkmcnt(0)
	v_add_f32_e32 v2, v2, v3
	v_cndmask_b32_e32 v76, v225, v76, vcc
	v_lshlrev_b32_e32 v83, 2, v76
	ds_bpermute_b32 v3, v83, v2
	v_xor_b32_e32 v76, 1, v225
	v_cmp_lt_i32_e32 vcc, v76, v0
	s_nop 1
	v_cndmask_b32_e32 v0, v225, v76, vcc
	v_lshlrev_b32_e32 v84, 2, v0
	s_waitcnt lgkmcnt(0)
	v_add_f32_e32 v0, v2, v3
	ds_bpermute_b32 v2, v84, v0
	v_cmp_eq_u32_e32 vcc, 0, v78
	s_and_saveexec_b64 s[0:1], vcc
	s_cbranch_execz .LBB0_786
	v_readlane_b32 s36, v244, 55
	v_readlane_b32 s37, v244, 56
	s_waitcnt lgkmcnt(0)
	v_add_f32_e32 v0, v0, v2
	v_mov_b32_e32 v2, v1
	v_lshl_add_u64 v[76:77], v[72:73], 4, s[36:37]
	v_mov_b32_e32 v3, v1
	global_store_dwordx4 v[76:77], v[0:3], off

; __global__ void __launch_bounds__(512, 2) fwd_mega(Params p, int ph_lo, int ph_hi, int coop) {
;     ...
;   for (int ph = ph_lo; ph < ph_hi; ++ph) {
;     run_phase(p, ph, lds, nsa_cnt_s, p4_stage, false);
;     ...
;     if ((REP_MASK >> (ph % PH_PER_LAYER)) & 1) { xcd_barrier(xb); run_phase(p, ph, lds, nsa_cnt_s, p4_stage, true); }
;     ...
;     for (int e = 0; e < EXTRA_SYNCS; ++e) xcd_barrier(xb);
;     ...
;     if (coop && ph + 1 < ph_hi) {
;       if (coop & 2) cg::this_grid().sync();
;       else xcd_barrier(xb);
;     }
.LBB0_915:
	s_add_i32 s92, s92, 1
	s_and_b32 s100, s92, 7
	s_lshr_b32 s101, s92, 3
	s_mul_i32 s101, s101, 3
	s_cmp_eq_u32 s100, 0
	s_cbranch_scc1 .Llatch_set
	s_add_i32 s101, s101, 2
	s_cmp_eq_u32 s100, 6
	s_cselect_b32 s101, s101, 0
.Llatch_set:
	s_mov_b32 s100, s101
	s_cmp_ge_i32 s92, s93
	s_cselect_b64 s[0:1], -1, 0
	s_cmp_lt_i32 s92, s93
	s_waitcnt lgkmcnt(0)
	v_readlane_b32 s26, v244, 1
	s_cselect_b64 s[4:5], -1, 0
	v_readlane_b32 s27, v244, 2
	s_and_b64 s[4:5], s[26:27], s[4:5]
	s_andn2_b64 vcc, exec, s[4:5]
	s_cbranch_vccz .LBB0_916
	s_getpc_b64 s[98:99]

; DEVI unsigned xb_ld(unsigned* p) { return __hip_atomic_load(p, __ATOMIC_RELAXED, __HIP_MEMORY_SCOPE_AGENT); }
; DEVI unsigned xb_add(unsigned* p, unsigned v) { return __hip_atomic_fetch_add(p, v, __ATOMIC_RELAXED, __HIP_MEMORY_SCOPE_AGENT); }
; #define XB_SPIN(cond, bar) do { unsigned _sp = 0; while (cond) { __builtin_amdgcn_s_sleep(1); \
;     if ((++_sp & 255u) == 0u) { if (xb_ld(&(bar)[XB_TMO])) break; if (_sp > XB_SPIN_CAP) { atomicAdd(&(bar)[XB_TMO], 1u); break; } } } } while (0)
; DEVI void xcd_barrier(const XcdBarrier& b) {
;   asm volatile("s_waitcnt vmcnt(0)" ::: "memory");
;   __syncthreads();
;   if (threadIdx.x == 0) {
;     unsigned* bar = b.bar;
;     __builtin_amdgcn_s_waitcnt(0);
;     unsigned nloc = b.st[0], nx = b.st[1];
;     if (nloc == 0u) { xcd_barrier_complete(bar, b.x, nloc, nx); b.st[0] = nloc; b.st[1] = nx; }
;     const unsigned old = xb_add(&bar[XB_XSUB(b.x)], 1u);
;     const unsigned gen = old / nloc;
;     if (old + 1u == (gen + 1u) * nloc) {
;       __builtin_amdgcn_fence(__ATOMIC_RELEASE, "agent");
;       asm volatile("s_waitcnt vmcnt(0)" ::: "memory");
;       const unsigned og = xb_add(&bar[XB_TOP], 1u);
;       const unsigned tg = og / nx;
;       if (og + 1u == (tg + 1u) * nx) xb_add(&bar[XB_TOPGEN], 1u);
;       else XB_SPIN(xb_ld(&bar[XB_TOPGEN]) == tg, bar);
.LBB0_962:
	s_mov_b32 s101, 0
	s_and_b32 s20, s92, 7
	s_cmp_eq_u32 s20, 1
	s_cbranch_scc1 .Lxb_global
	v_readfirstlane_b32 s20, v246
	s_bcnt1_i32_b32 s20, s20
	s_cmp_lg_u32 s20, 1
	s_cbranch_scc1 .Lxb_global
	v_readfirstlane_b32 s20, v247
	s_bcnt1_i32_b32 s20, s20
	s_cmp_lg_u32 s20, 1
	s_cbranch_scc1 .Lxb_global
	v_readfirstlane_b32 s20, v248
	s_bcnt1_i32_b32 s20, s20
	s_cmp_lg_u32 s20, 1
	s_cbranch_scc1 .Lxb_global
	v_readfirstlane_b32 s20, v249
	s_bcnt1_i32_b32 s20, s20
	s_cmp_lg_u32 s20, 1
	s_cbranch_scc1 .Lxb_global
	v_readfirstlane_b32 s20, v250
	s_bcnt1_i32_b32 s20, s20
	s_cmp_lg_u32 s20, 1
	s_cbranch_scc1 .Lxb_global
	v_readfirstlane_b32 s20, v251
	s_bcnt1_i32_b32 s20, s20
	s_cmp_lg_u32 s20, 1
	s_cbranch_scc1 .Lxb_global
	v_readfirstlane_b32 s20, v252
	s_bcnt1_i32_b32 s20, s20
	s_cmp_lg_u32 s20, 1
	s_cbranch_scc1 .Lxb_global
	v_readfirstlane_b32 s20, v253
	s_bcnt1_i32_b32 s20, s20
	s_cmp_lg_u32 s20, 1
	s_cbranch_scc1 .Lxb_global
	s_and_b32 s20, s92, 7
	s_cmp_eq_u32 s20, 6
	s_cbranch_scc1 .Lxb_split
	s_cmp_eq_u32 s20, 0
	s_cbranch_scc0 .Lxb_local_leader
.Lxb_split:
	s_mov_b32 s101, 1
